# code placement: 8 bytes of unreachable padding before the original pass-2 block (same instructions as previous best)
# speedup vs baseline: 1.0528x; 1.0047x over previous
.Lpv2_done:
	s_waitcnt vmcnt(0)
	s_branch .LBB0_74
	s_nop 0
	s_nop 0
